# attention unit epilogue: 16 row-per-lane dwordx2 O stores paired with v_permlane32_swap into 8 dwordx4 stores (same bytes, same addresses)
# speedup vs baseline: 1.0208x; 1.0065x over previous
.LBB0_1476:
	v_mov_b32_e32 v0, v182
	s_nop 1
	v_permlane32_swap_b32_e32 v182, v0
	v_add_f32_e32 v0, v182, v0
	v_rcp_f32_e32 v0, v0
	v_mov_b32_e32 v169, v1
	v_lshl_add_u64 v[66:67], v[166:167], 0, v[168:169]
	v_mbcnt_lo_u32_b32 v184, -1, 0
	v_mbcnt_hi_u32_b32 v184, -1, v184
	v_and_b32_e32 v184, 32, v184
	v_lshrrev_b32_e32 v184, 2, v184
	v_mov_b32_e32 v185, 0
	v_lshl_add_u64 v[66:67], v[66:67], 0, v[184:185]
	v_mul_f32_e32 v50, v50, v0
	v_mul_f32_e32 v51, v51, v0
	v_mul_f32_e32 v52, v52, v0
	v_mul_f32_e32 v53, v53, v0
	v_mul_f32_e32 v54, v54, v0
	v_mul_f32_e32 v55, v55, v0
	v_mul_f32_e32 v56, v56, v0
	v_mul_f32_e32 v57, v57, v0
	v_cvt_pk_bf16_f32 v50, v50, v51
	v_cvt_pk_bf16_f32 v51, v52, v53
	v_cvt_pk_bf16_f32 v52, v54, v55
	v_cvt_pk_bf16_f32 v53, v56, v57
	s_nop 1
	v_permlane32_swap_b32_e32 v50, v52
	v_permlane32_swap_b32_e32 v51, v53
	global_store_dwordx4 v[66:67], v[50:53], off
	v_mul_f32_e32 v58, v58, v0
	v_mul_f32_e32 v59, v59, v0
	v_mul_f32_e32 v60, v60, v0
	v_mul_f32_e32 v61, v61, v0
	v_mul_f32_e32 v62, v62, v0
	v_mul_f32_e32 v63, v63, v0
	v_mul_f32_e32 v64, v64, v0
	v_mul_f32_e32 v65, v65, v0
	v_cvt_pk_bf16_f32 v58, v58, v59
	v_cvt_pk_bf16_f32 v59, v60, v61
	v_cvt_pk_bf16_f32 v60, v62, v63
	v_cvt_pk_bf16_f32 v61, v64, v65
	s_nop 1
	v_permlane32_swap_b32_e32 v58, v60
	v_permlane32_swap_b32_e32 v59, v61
	global_store_dwordx4 v[66:67], v[58:61], off offset:32
	v_mul_f32_e32 v34, v34, v0
	v_mul_f32_e32 v35, v35, v0
	v_mul_f32_e32 v36, v36, v0
	v_mul_f32_e32 v37, v37, v0
	v_mul_f32_e32 v38, v38, v0
	v_mul_f32_e32 v39, v39, v0
	v_mul_f32_e32 v40, v40, v0
	v_mul_f32_e32 v41, v41, v0
	v_cvt_pk_bf16_f32 v34, v34, v35
	v_cvt_pk_bf16_f32 v35, v36, v37
	v_cvt_pk_bf16_f32 v36, v38, v39
	v_cvt_pk_bf16_f32 v37, v40, v41
	s_nop 1
	v_permlane32_swap_b32_e32 v34, v36
	v_permlane32_swap_b32_e32 v35, v37
	global_store_dwordx4 v[66:67], v[34:37], off offset:64
	v_mul_f32_e32 v42, v42, v0
	v_mul_f32_e32 v43, v43, v0
	v_mul_f32_e32 v44, v44, v0
	v_mul_f32_e32 v45, v45, v0
	v_mul_f32_e32 v46, v46, v0
	v_mul_f32_e32 v47, v47, v0
	v_mul_f32_e32 v48, v48, v0
	v_mul_f32_e32 v49, v49, v0
	v_cvt_pk_bf16_f32 v42, v42, v43
	v_cvt_pk_bf16_f32 v43, v44, v45
	v_cvt_pk_bf16_f32 v44, v46, v47
	v_cvt_pk_bf16_f32 v45, v48, v49
	s_nop 1
	v_permlane32_swap_b32_e32 v42, v44
	v_permlane32_swap_b32_e32 v43, v45
	global_store_dwordx4 v[66:67], v[42:45], off offset:96
	v_mul_f32_e32 v18, v18, v0
	v_mul_f32_e32 v19, v19, v0
	v_mul_f32_e32 v20, v20, v0
	v_mul_f32_e32 v21, v21, v0
	v_mul_f32_e32 v22, v22, v0
	v_mul_f32_e32 v23, v23, v0
	v_mul_f32_e32 v24, v24, v0
	v_mul_f32_e32 v25, v25, v0
	v_cvt_pk_bf16_f32 v18, v18, v19
	v_cvt_pk_bf16_f32 v19, v20, v21
	v_cvt_pk_bf16_f32 v20, v22, v23
	v_cvt_pk_bf16_f32 v21, v24, v25
	s_nop 1
	v_permlane32_swap_b32_e32 v18, v20
	v_permlane32_swap_b32_e32 v19, v21
	global_store_dwordx4 v[66:67], v[18:21], off offset:128
	v_mul_f32_e32 v26, v26, v0
	v_mul_f32_e32 v27, v27, v0
	v_mul_f32_e32 v28, v28, v0
	v_mul_f32_e32 v29, v29, v0
	v_mul_f32_e32 v30, v30, v0
	v_mul_f32_e32 v31, v31, v0
	v_mul_f32_e32 v32, v32, v0
	v_mul_f32_e32 v33, v33, v0
	v_cvt_pk_bf16_f32 v26, v26, v27
	v_cvt_pk_bf16_f32 v27, v28, v29
	v_cvt_pk_bf16_f32 v28, v30, v31
	v_cvt_pk_bf16_f32 v29, v32, v33
	s_nop 1
	v_permlane32_swap_b32_e32 v26, v28
	v_permlane32_swap_b32_e32 v27, v29
	global_store_dwordx4 v[66:67], v[26:29], off offset:160
	v_mul_f32_e32 v2, v2, v0
	v_mul_f32_e32 v3, v3, v0
	v_mul_f32_e32 v4, v4, v0
	v_mul_f32_e32 v5, v5, v0
	v_mul_f32_e32 v6, v6, v0
	v_mul_f32_e32 v7, v7, v0
	v_mul_f32_e32 v8, v8, v0
	v_mul_f32_e32 v9, v9, v0
	v_cvt_pk_bf16_f32 v2, v2, v3
	v_cvt_pk_bf16_f32 v3, v4, v5
	v_cvt_pk_bf16_f32 v4, v6, v7
	v_cvt_pk_bf16_f32 v5, v8, v9
	s_nop 1
	v_permlane32_swap_b32_e32 v2, v4
	v_permlane32_swap_b32_e32 v3, v5
	global_store_dwordx4 v[66:67], v[2:5], off offset:192
	v_mul_f32_e32 v10, v10, v0
	v_mul_f32_e32 v11, v11, v0
	v_mul_f32_e32 v12, v12, v0
	v_mul_f32_e32 v13, v13, v0
	v_mul_f32_e32 v14, v14, v0
	v_mul_f32_e32 v15, v15, v0
	v_mul_f32_e32 v16, v16, v0
	v_mul_f32_e32 v17, v17, v0
	v_cvt_pk_bf16_f32 v10, v10, v11
	v_cvt_pk_bf16_f32 v11, v12, v13
	v_cvt_pk_bf16_f32 v12, v14, v15
	v_cvt_pk_bf16_f32 v13, v16, v17
	s_nop 1
	v_permlane32_swap_b32_e32 v10, v12
	v_permlane32_swap_b32_e32 v11, v13
	global_store_dwordx4 v[66:67], v[10:13], off offset:224
	s_nop 1
	s_add_i32 s45, s45, s96
	s_add_i32 s38, s38, s39
	s_add_i32 s44, s44, s96
	s_cmpk_lt_i32 s45, 0x200
	s_cbranch_scc0 .LBB0_1501

.LBB0_1489:
	v_mov_b32_e32 v0, v182
	s_nop 1
	v_permlane32_swap_b32_e32 v182, v0
	v_add_f32_e32 v0, v182, v0
	v_rcp_f32_e32 v0, v0
	v_mov_b32_e32 v169, v1
	v_lshl_add_u64 v[66:67], v[166:167], 0, v[168:169]
	v_mbcnt_lo_u32_b32 v184, -1, 0
	v_mbcnt_hi_u32_b32 v184, -1, v184
	v_and_b32_e32 v184, 32, v184
	v_lshrrev_b32_e32 v184, 2, v184
	v_mov_b32_e32 v185, 0
	v_lshl_add_u64 v[66:67], v[66:67], 0, v[184:185]
	v_mul_f32_e32 v50, v50, v0
	v_mul_f32_e32 v51, v51, v0
	v_mul_f32_e32 v52, v52, v0
	v_mul_f32_e32 v53, v53, v0
	v_mul_f32_e32 v54, v54, v0
	v_mul_f32_e32 v55, v55, v0
	v_mul_f32_e32 v56, v56, v0
	v_mul_f32_e32 v57, v57, v0
	v_cvt_pk_bf16_f32 v50, v50, v51
	v_cvt_pk_bf16_f32 v51, v52, v53
	v_cvt_pk_bf16_f32 v52, v54, v55
	v_cvt_pk_bf16_f32 v53, v56, v57
	s_nop 1
	v_permlane32_swap_b32_e32 v50, v52
	v_permlane32_swap_b32_e32 v51, v53
	global_store_dwordx4 v[66:67], v[50:53], off
	v_mul_f32_e32 v58, v58, v0
	v_mul_f32_e32 v59, v59, v0
	v_mul_f32_e32 v60, v60, v0
	v_mul_f32_e32 v61, v61, v0
	v_mul_f32_e32 v62, v62, v0
	v_mul_f32_e32 v63, v63, v0
	v_mul_f32_e32 v64, v64, v0
	v_mul_f32_e32 v65, v65, v0
	v_cvt_pk_bf16_f32 v58, v58, v59
	v_cvt_pk_bf16_f32 v59, v60, v61
	v_cvt_pk_bf16_f32 v60, v62, v63
	v_cvt_pk_bf16_f32 v61, v64, v65
	s_nop 1
	v_permlane32_swap_b32_e32 v58, v60
	v_permlane32_swap_b32_e32 v59, v61
	global_store_dwordx4 v[66:67], v[58:61], off offset:32
	v_mul_f32_e32 v34, v34, v0
	v_mul_f32_e32 v35, v35, v0
	v_mul_f32_e32 v36, v36, v0
	v_mul_f32_e32 v37, v37, v0
	v_mul_f32_e32 v38, v38, v0
	v_mul_f32_e32 v39, v39, v0
	v_mul_f32_e32 v40, v40, v0
	v_mul_f32_e32 v41, v41, v0
	v_cvt_pk_bf16_f32 v34, v34, v35
	v_cvt_pk_bf16_f32 v35, v36, v37
	v_cvt_pk_bf16_f32 v36, v38, v39
	v_cvt_pk_bf16_f32 v37, v40, v41
	s_nop 1
	v_permlane32_swap_b32_e32 v34, v36
	v_permlane32_swap_b32_e32 v35, v37
	global_store_dwordx4 v[66:67], v[34:37], off offset:64
	v_mul_f32_e32 v42, v42, v0
	v_mul_f32_e32 v43, v43, v0
	v_mul_f32_e32 v44, v44, v0
	v_mul_f32_e32 v45, v45, v0
	v_mul_f32_e32 v46, v46, v0
	v_mul_f32_e32 v47, v47, v0
	v_mul_f32_e32 v48, v48, v0
	v_mul_f32_e32 v49, v49, v0
	v_cvt_pk_bf16_f32 v42, v42, v43
	v_cvt_pk_bf16_f32 v43, v44, v45
	v_cvt_pk_bf16_f32 v44, v46, v47
	v_cvt_pk_bf16_f32 v45, v48, v49
	s_nop 1
	v_permlane32_swap_b32_e32 v42, v44
	v_permlane32_swap_b32_e32 v43, v45
	global_store_dwordx4 v[66:67], v[42:45], off offset:96
	v_mul_f32_e32 v18, v18, v0
	v_mul_f32_e32 v19, v19, v0
	v_mul_f32_e32 v20, v20, v0
	v_mul_f32_e32 v21, v21, v0
	v_mul_f32_e32 v22, v22, v0
	v_mul_f32_e32 v23, v23, v0
	v_mul_f32_e32 v24, v24, v0
	v_mul_f32_e32 v25, v25, v0
	v_cvt_pk_bf16_f32 v18, v18, v19
	v_cvt_pk_bf16_f32 v19, v20, v21
	v_cvt_pk_bf16_f32 v20, v22, v23
	v_cvt_pk_bf16_f32 v21, v24, v25
	s_nop 1
	v_permlane32_swap_b32_e32 v18, v20
	v_permlane32_swap_b32_e32 v19, v21
	global_store_dwordx4 v[66:67], v[18:21], off offset:128
	v_mul_f32_e32 v26, v26, v0
	v_mul_f32_e32 v27, v27, v0
	v_mul_f32_e32 v28, v28, v0
	v_mul_f32_e32 v29, v29, v0
	v_mul_f32_e32 v30, v30, v0
	v_mul_f32_e32 v31, v31, v0
	v_mul_f32_e32 v32, v32, v0
	v_mul_f32_e32 v33, v33, v0
	v_cvt_pk_bf16_f32 v26, v26, v27
	v_cvt_pk_bf16_f32 v27, v28, v29
	v_cvt_pk_bf16_f32 v28, v30, v31
	v_cvt_pk_bf16_f32 v29, v32, v33
	s_nop 1
	v_permlane32_swap_b32_e32 v26, v28
	v_permlane32_swap_b32_e32 v27, v29
	global_store_dwordx4 v[66:67], v[26:29], off offset:160
	v_mul_f32_e32 v2, v2, v0
	v_mul_f32_e32 v3, v3, v0
	v_mul_f32_e32 v4, v4, v0
	v_mul_f32_e32 v5, v5, v0
	v_mul_f32_e32 v6, v6, v0
	v_mul_f32_e32 v7, v7, v0
	v_mul_f32_e32 v8, v8, v0
	v_mul_f32_e32 v9, v9, v0
	v_cvt_pk_bf16_f32 v2, v2, v3
	v_cvt_pk_bf16_f32 v3, v4, v5
	v_cvt_pk_bf16_f32 v4, v6, v7
	v_cvt_pk_bf16_f32 v5, v8, v9
	s_nop 1
	v_permlane32_swap_b32_e32 v2, v4
	v_permlane32_swap_b32_e32 v3, v5
	global_store_dwordx4 v[66:67], v[2:5], off offset:192
	v_mul_f32_e32 v10, v10, v0
	v_mul_f32_e32 v11, v11, v0
	v_mul_f32_e32 v12, v12, v0
	v_mul_f32_e32 v13, v13, v0
	v_mul_f32_e32 v14, v14, v0
	v_mul_f32_e32 v15, v15, v0
	v_mul_f32_e32 v16, v16, v0
	v_mul_f32_e32 v17, v17, v0
	v_cvt_pk_bf16_f32 v10, v10, v11
	v_cvt_pk_bf16_f32 v11, v12, v13
	v_cvt_pk_bf16_f32 v12, v14, v15
	v_cvt_pk_bf16_f32 v13, v16, v17
	s_nop 1
	v_permlane32_swap_b32_e32 v10, v12
	v_permlane32_swap_b32_e32 v11, v13
	global_store_dwordx4 v[66:67], v[10:13], off offset:224
	s_nop 1
	s_lshl_b32 s36, s30, 1
	v_mbcnt_lo_u32_b32 v3, -1, 0
	v_mbcnt_hi_u32_b32 v3, -1, v3
	s_mov_b32 s37, s5
	v_add_u32_e32 v0, s95, v3
	v_ashrrev_i32_e32 v14, 4, v0
	v_add_u32_e32 v4, s24, v14
	v_ashrrev_i32_e32 v5, 31, v4
	v_lshlrev_b64 v[4:5], 11, v[4:5]
	v_ashrrev_i32_e32 v2, 3, v0
	v_lshl_add_u64 v[4:5], s[10:11], 0, v[4:5]
	v_lshlrev_b32_e32 v10, 4, v3
	v_lshl_add_u64 v[4:5], v[4:5], 0, s[36:37]
	v_and_b32_e32 v6, 0xf0, v10
	v_mov_b32_e32 v7, v1
	v_add_u32_e32 v12, s30, v2
	v_lshl_add_u64 v[4:5], v[4:5], 0, v[6:7]
	v_ashrrev_i32_e32 v13, 31, v12
	v_add_u32_e32 v8, s24, v2
	v_lshlrev_b64 v[12:13], 16, v[12:13]
	global_load_dwordx4 v[98:101], v[4:5], off
	v_add_co_u32_e32 v4, vcc, s41, v4
	v_ashrrev_i32_e32 v9, 31, v8
	v_lshl_add_u64 v[12:13], s[14:15], 0, v[12:13]
	v_addc_co_u32_e32 v5, vcc, 0, v5, vcc
	v_lshlrev_b64 v[8:9], 7, v[8:9]
	global_load_dwordx4 v[102:105], v[4:5], off
	v_lshl_add_u64 v[4:5], s[24:25], 1, v[12:13]
	v_readfirstlane_b32 s25, v0
	v_lshl_add_u64 v[8:9], s[12:13], 0, v[8:9]
	v_and_b32_e32 v10, 0x70, v10
	v_mov_b32_e32 v11, v1
	s_ashr_i32 s25, s25, 1
	v_lshl_add_u64 v[8:9], v[8:9], 0, v[10:11]
	v_lshl_add_u64 v[4:5], v[4:5], 0, v[10:11]
	s_lshl_b32 s30, s46, 8
	s_andn2_b32 s25, s25, 31
	global_load_dwordx4 v[106:109], v[8:9], off
	global_load_dwordx4 v[126:129], v[4:5], off
	v_add_co_u32_e32 v4, vcc, s42, v4
	s_add_i32 s30, s25, s30
	s_nop 0
	v_addc_co_u32_e32 v5, vcc, 0, v5, vcc
	v_and_b32_e32 v12, 31, v3
	s_add_i32 s24, s30, s24
	global_load_dwordx4 v[150:153], v[4:5], off
	v_or_b32_e32 v4, s24, v12
	v_ashrrev_i32_e32 v5, 31, v4
	v_lshlrev_b64 v[8:9], 11, v[4:5]
	v_bfe_u32 v13, v3, 5, 1
	v_lshl_add_u64 v[8:9], s[6:7], 0, v[8:9]
	v_lshl_add_u64 v[166:167], v[8:9], 0, s[36:37]
	v_lshlrev_b32_e32 v0, 4, v13
	v_lshl_add_u64 v[8:9], v[166:167], 0, v[0:1]
	global_load_dwordx4 v[110:113], v[8:9], off
	global_load_dwordx4 v[114:117], v[8:9], off offset:32
	global_load_dwordx4 v[118:121], v[8:9], off offset:64
	global_load_dwordx4 v[122:125], v[8:9], off offset:96
	global_load_dwordx4 v[130:133], v[8:9], off offset:128
	global_load_dwordx4 v[134:137], v[8:9], off offset:160
	global_load_dwordx4 v[138:141], v[8:9], off offset:192
	global_load_dwordx4 v[142:145], v[8:9], off offset:224
	v_lshlrev_b64 v[4:5], 10, v[4:5]
	v_lshl_add_u64 v[4:5], s[8:9], 0, v[4:5]
	s_lshl_b32 s24, s31, 1
	s_mov_b32 s25, s5
	v_lshl_add_u64 v[4:5], v[4:5], 0, s[24:25]
	v_lshl_add_u64 v[4:5], v[4:5], 0, v[0:1]
	global_load_dwordx4 v[146:149], v[4:5], off
	global_load_dwordx4 v[154:157], v[4:5], off offset:32
	global_load_dwordx4 v[158:161], v[4:5], off offset:64
	global_load_dwordx4 v[162:165], v[4:5], off offset:96
	s_and_b32 s24, s44, 7
	v_and_b32_e32 v4, 19, v3
	v_lshlrev_b32_e32 v5, 1, v3
	v_lshrrev_b32_e32 v3, 1, v3
	s_lshl_b32 s31, s24, 8
	v_mad_u64_u32 v[170:171], s[24:25], v14, s40, v[6:7]
	v_and_b32_e32 v5, 8, v5
	v_and_b32_e32 v3, 4, v3
	v_or3_b32 v3, v4, v5, v3
	v_add_u32_e32 v4, 0, v170
	v_mad_u64_u32 v[172:173], s[24:25], v2, s40, v[10:11]
	s_barrier
	s_waitcnt vmcnt(16)
	ds_write_b128 v4, v[98:101]
	s_waitcnt vmcnt(15)
	ds_write_b128 v4, v[102:105] offset:12800
	v_add_u32_e32 v4, 0, v172
	v_mul_u32_u24_e32 v3, 0x190, v3
	v_add3_u32 v171, 0, v3, v0
	v_ashrrev_i32_e32 v3, 31, v2
	v_mov_b32_e32 v15, v1
	v_lshlrev_b32_e32 v168, 3, v13
	v_or_b32_e32 v173, s30, v12
	v_mov_b32_e32 v8, v1
	v_mov_b32_e32 v9, v1
	v_mov_b32_e32 v13, v1
	s_waitcnt vmcnt(14)
	ds_write_b128 v4, v[106:109] offset:256
	v_lshlrev_b32_e32 v4, 8, v2
	v_sub_u32_e32 v169, v172, v4
	v_add_u32_e32 v4, 0, v169
	s_waitcnt vmcnt(13)
	ds_write_b128 v4, v[126:129] offset:25600
	s_waitcnt vmcnt(12)
	ds_write_b128 v4, v[150:153] offset:34816
	v_mul_u32_u24_e32 v4, 0x90, v12
	v_add3_u32 v181, 0, v4, v0
	v_lshl_add_u64 v[4:5], v[2:3], 0, s[34:35]
	v_lshlrev_b64 v[4:5], 7, v[4:5]
	v_or_b32_e32 v4, v4, v10
	v_lshl_add_u64 v[174:175], v[4:5], 0, s[16:17]
	v_add_u32_e32 v4, s34, v14
	v_ashrrev_i32_e32 v5, 31, v4
	v_lshlrev_b64 v[2:3], 16, v[2:3]
	v_lshlrev_b64 v[4:5], 11, v[4:5]
	v_lshl_add_u64 v[2:3], s[28:29], 0, v[2:3]
	v_or_b32_e32 v4, s4, v4
	v_lshl_add_u64 v[2:3], v[2:3], 0, v[10:11]
	v_mov_b32_e32 v14, v1
	v_lshl_add_u64 v[176:177], v[4:5], 0, v[6:7]
	v_lshl_add_u64 v[178:179], v[2:3], 0, s[26:27]
	v_mov_b32_e32 v0, v1
	v_mov_b32_e32 v2, v1
	v_mov_b32_e32 v3, v1
	v_mov_b32_e32 v4, v1
	v_mov_b32_e32 v5, v1
	v_mov_b32_e32 v6, v1
	v_mov_b32_e32 v10, v1
	v_mov_b32_e32 v12, v1
	v_mov_b64_e32 v[64:65], v[14:15]
	v_mov_b64_e32 v[48:49], v[14:15]
	v_mov_b64_e32 v[32:33], v[14:15]
	s_lshl_b32 s46, s46, 2
	v_mov_b64_e32 v[62:63], v[12:13]
	v_mov_b64_e32 v[60:61], v[10:11]
	v_mov_b64_e32 v[58:59], v[8:9]
	v_mov_b64_e32 v[56:57], v[6:7]
	v_mov_b64_e32 v[54:55], v[4:5]
	v_mov_b64_e32 v[52:53], v[2:3]
	v_mov_b64_e32 v[50:51], v[0:1]
	v_mov_b64_e32 v[46:47], v[12:13]
	v_mov_b64_e32 v[44:45], v[10:11]
	v_mov_b64_e32 v[42:43], v[8:9]
	v_mov_b64_e32 v[40:41], v[6:7]
	v_mov_b64_e32 v[38:39], v[4:5]
	v_mov_b64_e32 v[36:37], v[2:3]
	v_mov_b64_e32 v[34:35], v[0:1]
	v_mov_b64_e32 v[30:31], v[12:13]
	v_mov_b64_e32 v[28:29], v[10:11]
	v_mov_b64_e32 v[26:27], v[8:9]
	v_mov_b64_e32 v[24:25], v[6:7]
	v_mov_b64_e32 v[22:23], v[4:5]
	v_mov_b64_e32 v[20:21], v[2:3]
	v_mov_b64_e32 v[18:19], v[0:1]
	v_mov_b64_e32 v[16:17], v[14:15]
	s_addk_i32 s31, 0x100
	s_mov_b32 s36, 1
	s_mov_b32 s37, 0
	s_add_i32 s46, s46, 4
	s_or_b32 s47, s30, 31
	v_mov_b32_e32 v182, 0
	v_mov_b32_e32 v183, 0xf149f2ca
	v_mov_b64_e32 v[14:15], v[12:13]
	v_mov_b64_e32 v[12:13], v[10:11]
	v_mov_b64_e32 v[10:11], v[8:9]
	v_mov_b64_e32 v[8:9], v[6:7]
	v_mov_b64_e32 v[6:7], v[4:5]
	v_mov_b64_e32 v[4:5], v[2:3]
	v_mov_b64_e32 v[2:3], v[0:1]
	s_waitcnt lgkmcnt(0)
	s_barrier
	s_branch .LBB0_1491
